# DA loop: next tile K/V global loads issued before the end-of-step barrier instead of after it
# baseline (speedup 1.0000x reference)
; template <int MODE>
; DI void attn_unit(LAS unsigned char* lds, const bf16_t* Qg, int ldq, const bf16_t* Kg, int ldk, const bf16_t* VTg, int ldvt, bf16_t* Og, int ldo,
;                   int q0, int NT, const float* gout, const float* relb, float lam, float osc, const float* qgain) {
;     ...
;     u32x4 kr[KJ], vr[VJ];
;     ...
;     AT_GLOAD(AT_KEY0(0)); AT_LSTORE(0, 0);
;     __syncthreads();
;     float mhat = 0.f, lrun = 0.f, R = 0.f;
;     f32x16 negm;
; #pragma unroll
;     for (int i = 0; i < 16; ++i) negm[i] = c15;
;     f32x16 o[NDB];
; #pragma unroll
;     for (int d = 0; d < NDB; ++d)
; #pragma unroll
;         for (int i = 0; i < 16; ++i) o[d][i] = 0.f;
;     const bool skew = (MODE != 2) && (wid >= 4);
;     u32x4 pk[4];
; #pragma unroll
;     for (int j = 0; j < 4; ++j) pk[j] = (u32x4){0u, 0u, 0u, 0u};
;     ...
;         if (t + 1 < NT) AT_GLOAD(AT_KEY0(t + 1));
.LBB0_179:
	s_or_b64 exec, exec, s[10:11]
	v_add_f32_e32 v157, v161, v157
	v_pk_add_f32 v[156:157], v[156:157], v[0:1]
	v_add_f32_e32 v155, v155, v153
	v_pk_add_f32 v[156:157], v[156:157], v[156:157] op_sel_hi:[0,1]
	v_mov_b32_e32 v153, v157
	v_pk_add_f32 v[152:153], v[154:155], v[152:153]
	v_add_f32_e32 v115, v115, v113
	v_pk_add_f32 v[152:153], v[152:153], v[152:153] op_sel_hi:[0,1]
	v_mov_b32_e32 v113, v153
	v_pk_add_f32 v[112:113], v[114:115], v[112:113]
	v_add_f32_e32 v111, v111, v109
	v_pk_add_f32 v[112:113], v[112:113], v[112:113] op_sel_hi:[0,1]
	v_mov_b32_e32 v109, v113
	v_pk_add_f32 v[108:109], v[110:111], v[108:109]
	v_add_f32_e32 v107, v160, v81
	v_pk_add_f32 v[108:109], v[108:109], v[108:109] op_sel_hi:[0,1]
	v_mov_b32_e32 v105, v109
	v_pk_add_f32 v[104:105], v[106:107], v[104:105]
	v_add_f32_e32 v81, v79, v77
	v_pk_add_f32 v[104:105], v[104:105], v[104:105] op_sel_hi:[0,1]
	v_mov_b32_e32 v79, v105
	v_pk_add_f32 v[78:79], v[80:81], v[78:79]
	v_add_f32_e32 v77, v75, v73
	v_pk_add_f32 v[78:79], v[78:79], v[78:79] op_sel_hi:[0,1]
	v_mov_b32_e32 v75, v79
	v_pk_add_f32 v[74:75], v[76:77], v[74:75]
	s_mov_b32 s2, 0xcc00
	v_pk_add_f32 v[74:75], v[74:75], v[74:75] op_sel_hi:[0,1]
	v_add_f32_e32 v73, v71, v69
	v_mov_b32_e32 v71, v75
	v_add3_u32 v0, v185, v186, s2
	v_pk_add_f32 v[70:71], v[72:73], v[70:71]
	s_waitcnt vmcnt(0)
	ds_write2_b64 v0, v[140:141], v[142:143] offset1:1
	v_add3_u32 v0, v185, v187, s2
	v_pk_add_f32 v[70:71], v[70:71], v[70:71] op_sel_hi:[0,1]
	ds_write2_b64 v0, v[144:145], v[146:147] offset1:1
	v_add_u32_e32 v0, v82, v83
	v_ashrrev_i32_e32 v70, 4, v0
	v_and_b32_e32 v0, -16, v0
	v_mov_b32_e32 v69, v71
	v_sub_u32_e32 v0, v82, v0
	v_pk_add_f32 v[152:153], v[68:69], 0 op_sel_hi:[1,0]
	v_lshlrev_b32_e32 v72, 3, v0
	v_lshlrev_b32_e32 v193, 4, v0
	v_add_u32_e32 v0, s21, v150
	v_lshlrev_b32_e32 v69, 2, v159
	s_lshl_b32 s12, s29, 1
	s_lshr_b32 s19, s24, 6
	v_sub_u32_e32 v0, v0, v69
	s_lshl_b32 s2, s27, 7
	s_add_i32 s14, s12, 2
	s_add_i32 s18, s19, 1
	s_addk_i32 s24, 0xff41
	v_subrev_u32_e32 v0, s2, v0
	s_lshl_b32 s25, s29, 9
	s_lshl_b64 s[2:3], s[16:17], 12
	s_add_u32 s2, s20, s2
	s_addc_u32 s3, 0, s3
	v_subrev_u32_e32 v0, s25, v0
	s_add_u32 s2, s2, 0x18000100
	v_add_u32_e32 v194, 0, v0
	s_addc_u32 s3, s3, 0
	v_and_b32_e32 v0, 7, v82
	v_lshl_add_u64 v[76:77], s[2:3], 0, v[100:101]
	v_lshlrev_b32_e32 v0, 4, v0
	v_lshl_add_u64 v[154:155], v[76:77], 0, v[0:1]
	v_lshl_add_u64 v[76:77], s[2:3], 0, v[102:103]
	s_add_u32 s2, s8, s28
	s_addc_u32 s3, s9, 0
	v_mul_u32_u24_e32 v191, 0x88, v159
	v_ashrrev_i32_e32 v159, 31, v158
	s_add_u32 s2, s2, 0x8080400
	v_ashrrev_i32_e32 v71, 31, v70
	v_lshlrev_b32_e32 v74, 3, v162
	v_mul_lo_u32 v192, v70, s56
	v_lshl_add_u64 v[156:157], v[76:77], 0, v[0:1]
	v_lshlrev_b64 v[76:77], 12, v[158:159]
	s_addc_u32 s3, s3, 0
	v_lshlrev_b64 v[70:71], 12, v[70:71]
	v_sub_f32_e32 v68, v66, v152
	v_ashrrev_i32_e32 v73, 31, v72
	v_ashrrev_i32_e32 v75, 31, v74
	v_lshl_add_u64 v[76:77], s[2:3], 0, v[76:77]
	v_lshl_add_u64 v[70:71], s[2:3], 0, v[70:71]
	s_mov_b32 s13, 1
	s_mov_b32 s15, 2
	s_mov_b32 s21, s29
	v_lshl_add_u64 v[158:159], v[74:75], 1, v[76:77]
	v_lshl_add_u64 v[160:161], v[72:73], 1, v[70:71]
	s_movk_i32 s28, 0xff00
	s_mov_b32 s29, 64
	v_mov_b32_e32 v69, v68
	v_mov_b32_e32 v70, v68
	v_mov_b32_e32 v71, v68
	v_mov_b32_e32 v72, v68
	v_mov_b32_e32 v73, v68
	v_mov_b32_e32 v74, v68
	v_mov_b32_e32 v75, v68
	v_mov_b32_e32 v76, v68
	v_mov_b32_e32 v77, v68
	v_mov_b32_e32 v78, v68
	v_mov_b32_e32 v79, v68
	v_mov_b32_e32 v80, v68
	v_mov_b32_e32 v81, v68
	v_mov_b32_e32 v82, v68
	v_mov_b32_e32 v83, v68
	v_readlane_b32 s2, v253, 40
	v_readlane_b32 s3, v253, 41
	s_nop 1
	v_lshl_add_u64 v[154:155], s[2:3], 0, v[154:155]
	v_lshl_add_u64 v[156:157], s[2:3], 0, v[156:157]
	v_lshl_add_u64 v[158:159], s[2:3], 0, v[158:159]
	v_lshl_add_u64 v[160:161], s[2:3], 0, v[160:161]
	s_cmp_lt_u32 s15, s14
	s_cselect_b64 s[8:9], -1, 0
	s_cbranch_scc0 .Lda_noload0
	global_load_dwordx4 v[132:135], v[160:161], off
	global_load_dwordx4 v[136:139], v[158:159], off
	global_load_dwordx4 v[140:143], v[154:155], off
	global_load_dwordx4 v[144:147], v[156:157], off
; #define LAS __attribute__((address_space(3)))
; #define MFMA32(a, b, c) __builtin_amdgcn_mfma_f32_32x32x16_bf16((a), (b), (c), 0, 0, 0)
; template <int MODE>
; DI void attn_unit(LAS unsigned char* lds, const bf16_t* Qg, int ldq, const bf16_t* Kg, int ldk, const bf16_t* VTg, int ldvt, bf16_t* Og, int ldo,
;                   int q0, int NT, const float* gout, const float* relb, float lam, float osc, const float* qgain) {
;     ...
;     auto pvdo = [&](const int vbi, const u32x4 (&pp)[4]) {
;         const LAS unsigned char* Vb = lds + VB0 + vbi * VBSZ + (r32 + (MODE == 2 ? mm * 64 : 0)) * VSTR + hi * 8;
; #pragma unroll
;         for (int d = 0; d < NDB; ++d)
; #pragma unroll
;             for (int ks = 0; ks < 4; ++ks) { const int kb = 32 * (ks >> 1) + 16 * (ks & 1);
;                 const s16x4 lo = *(const LAS s16x4*)(Vb + d * 32 * VSTR + kb * 2), hh = *(const LAS s16x4*)(Vb + d * 32 * VSTR + kb * 2 + 16);
;                 const bf16x8 vf = __builtin_shufflevector(lo, hh, 0, 1, 2, 3, 4, 5, 6, 7);
;                 o[d] = MFMA32(vf, __builtin_bit_cast(bf16x8, pp[ks]), o[d]); }
;     };
;     ...
;     for (int t = 0; t < NT; ++t) {
;         const int cur = t & 1;
;         const int vnext = vcur == 2 ? 0 : vcur + 1, vprev = vcur == 0 ? 2 : vcur - 1;
;         if (MODE == 2 && SB_EARLY && t > 0) {
;             const LAS unsigned* fl = (const LAS unsigned*)(lds + FLG) + ((t - 1) & 1) * 8; unsigned any = 0;
; #pragma unroll
;             for (int w = 0; w < 8; ++w) any |= fl[w];
;             if (any == 0u) break;
;         }
;         if (t + 1 < NT) AT_GLOAD(AT_KEY0(t + 1));
;         const int key0 = AT_KEY0(t);
;         bool active;
;         if (MODE == 2) active = (NT - 1 - t) <= TD; else active = t < ntw;
;         bool alive = true;
;         if (MODE == 2) alive = !active || __any(R > -150.f);
;         if (skew && t >= 1 && (t - 1) < ntw) pvdo(vprev, pk);
.Lda_noload0:
	s_waitcnt lgkmcnt(0)
	s_barrier
	s_branch .LBB0_182
.LBB0_180:
	s_mul_i32 s2, s13, 0x4400
	v_add_u32_e32 v0, s2, v185
	s_mov_b32 s2, 0x8800
	v_add3_u32 v100, v0, v186, s2
	v_add3_u32 v0, v0, v187, s2
	ds_write2_b64 v100, v[140:141], v[142:143] offset1:1
	ds_write2_b64 v0, v[144:145], v[146:147] offset1:1
.LBB0_181:
	s_add_i32 s15, s15, 1
	s_addk_i32 s28, 0x100
	s_mov_b64 s[2:3], 0x40000
	s_add_i32 s29, s29, 64
	v_lshl_add_u64 v[154:155], v[154:155], 0, s[34:35]
	v_lshl_add_u64 v[156:157], v[156:157], 0, s[34:35]
	v_lshl_add_u64 v[158:159], v[158:159], 0, s[2:3]
	v_lshl_add_u64 v[160:161], v[160:161], 0, s[2:3]
	s_cmp_lt_u32 s15, s14
	s_cselect_b64 s[8:9], -1, 0
	s_cbranch_scc0 .Lda_noload
	s_cmp_eq_u32 s25, s28
	s_cbranch_scc1 .Lda_noload
	global_load_dwordx4 v[132:135], v[160:161], off
	global_load_dwordx4 v[136:139], v[158:159], off
	global_load_dwordx4 v[140:143], v[154:155], off
	global_load_dwordx4 v[144:147], v[156:157], off
.Lda_noload:
	s_cmp_eq_u32 s25, s28
	s_waitcnt lgkmcnt(0)
	s_barrier
	s_cbranch_scc1 .LBB0_203
.LBB0_182:
.LBB0_185:
.LBB0_187:
.LBB0_188:
	s_add_i32 s2, s15, -1
	s_cmp_le_u32 s2, s18
	s_cselect_b64 s[10:11], -1, 0
	s_and_b64 s[10:11], s[0:1], s[10:11]
	s_andn2_b64 vcc, exec, s[10:11]
	s_cbranch_vccnz .LBB0_190
	s_mul_i32 s3, s13, 0x4400
	s_addk_i32 s3, 0xbc00
	s_cmp_lg_u32 s13, 0
	s_cselect_b32 s3, s3, 0x8800
	v_add_u32_e32 v0, s3, v67
	v_add_u32_e32 v236, 0x8800, v0
	v_add_u32_e32 v237, 0x9800, v0
	v_add_u32_e32 v238, 0xa800, v0
	v_add_u32_e32 v239, 0xb800, v0
	ds_read2_b64 v[212:215], v236 offset1:2
	ds_read2_b64 v[216:219], v236 offset0:4 offset1:6
	ds_read2_b64 v[220:223], v236 offset0:8 offset1:10
	ds_read2_b64 v[224:227], v236 offset0:12 offset1:14
	s_waitcnt lgkmcnt(2)
	v_mfma_f32_32x32x16_bf16 v[50:65], v[212:215], v[96:99], v[50:65]
	v_mfma_f32_32x32x16_bf16 v[50:65], v[216:219], v[92:95], v[50:65]
	ds_read2_b64 v[212:215], v237 offset0:32 offset1:34
	ds_read2_b64 v[216:219], v237 offset0:36 offset1:38
	s_waitcnt lgkmcnt(2)
	v_mfma_f32_32x32x16_bf16 v[50:65], v[220:223], v[88:91], v[50:65]
	v_mfma_f32_32x32x16_bf16 v[50:65], v[224:227], v[84:87], v[50:65]
	ds_read2_b64 v[220:223], v237 offset0:40 offset1:42
	ds_read2_b64 v[224:227], v237 offset0:44 offset1:46
	s_waitcnt lgkmcnt(2)
	v_mfma_f32_32x32x16_bf16 v[34:49], v[212:215], v[96:99], v[34:49]
	v_mfma_f32_32x32x16_bf16 v[34:49], v[216:219], v[92:95], v[34:49]
	ds_read2_b64 v[212:215], v238 offset0:64 offset1:66
	ds_read2_b64 v[216:219], v238 offset0:68 offset1:70
	s_waitcnt lgkmcnt(2)
	v_mfma_f32_32x32x16_bf16 v[34:49], v[220:223], v[88:91], v[34:49]
	v_mfma_f32_32x32x16_bf16 v[34:49], v[224:227], v[84:87], v[34:49]
	ds_read2_b64 v[220:223], v238 offset0:72 offset1:74
	ds_read2_b64 v[224:227], v238 offset0:76 offset1:78
	s_waitcnt lgkmcnt(2)
	v_mfma_f32_32x32x16_bf16 v[18:33], v[212:215], v[96:99], v[18:33]
	v_mfma_f32_32x32x16_bf16 v[18:33], v[216:219], v[92:95], v[18:33]
	ds_read2_b64 v[212:215], v239 offset0:96 offset1:98
	ds_read2_b64 v[216:219], v239 offset0:100 offset1:102
	s_waitcnt lgkmcnt(2)
	v_mfma_f32_32x32x16_bf16 v[18:33], v[220:223], v[88:91], v[18:33]
	v_mfma_f32_32x32x16_bf16 v[18:33], v[224:227], v[84:87], v[18:33]
	ds_read2_b64 v[220:223], v239 offset0:104 offset1:106
	ds_read2_b64 v[224:227], v239 offset0:108 offset1:110
	s_waitcnt lgkmcnt(2)
	v_mfma_f32_32x32x16_bf16 v[2:17], v[212:215], v[96:99], v[2:17]
	v_mfma_f32_32x32x16_bf16 v[2:17], v[216:219], v[92:95], v[2:17]
	s_waitcnt lgkmcnt(0)
	v_mfma_f32_32x32x16_bf16 v[2:17], v[220:223], v[88:91], v[2:17]
	v_mfma_f32_32x32x16_bf16 v[2:17], v[224:227], v[84:87], v[2:17]
